# stagger odd WGs 10us at branch-GEMM phase start (overlap epilogue HBM traffic with other WGs main loops)
# baseline (speedup 1.0000x reference)
.LBB0_508:
	v_readlane_b32 s98, v254, 0
	s_nop 3
	s_bitcmp1_b32 s98, 0
	s_cbranch_scc0 .Lstag_done_0
	s_memrealtime s[98:99]
	s_waitcnt lgkmcnt(0)
	s_mov_b32 s100, s98
.Lstag_spin_0:
	s_sleep 8
	s_memrealtime s[98:99]
	s_waitcnt lgkmcnt(0)
	s_sub_u32 s98, s98, s100
	s_cmp_lt_u32 s98, 1000
	s_cbranch_scc1 .Lstag_spin_0

	.amdhsa_kernel _Z6mk_fwd4Args
		.amdhsa_group_segment_fixed_size 0
		.amdhsa_private_segment_fixed_size 0
		.amdhsa_kernarg_size 448
		.amdhsa_user_sgpr_count 2
		.amdhsa_user_sgpr_dispatch_ptr 0
		.amdhsa_user_sgpr_queue_ptr 0
		.amdhsa_user_sgpr_kernarg_segment_ptr 1
		.amdhsa_user_sgpr_dispatch_id 0
		.amdhsa_user_sgpr_kernarg_preload_length 0
		.amdhsa_user_sgpr_kernarg_preload_offset 0
		.amdhsa_user_sgpr_private_segment_size 0
		.amdhsa_uses_dynamic_stack 0
		.amdhsa_enable_private_segment 0
		.amdhsa_system_sgpr_workgroup_id_x 1
		.amdhsa_system_sgpr_workgroup_id_y 0
		.amdhsa_system_sgpr_workgroup_id_z 0
		.amdhsa_system_sgpr_workgroup_info 0
		.amdhsa_system_vgpr_workitem_id 2
		.amdhsa_next_free_vgpr 256
		.amdhsa_next_free_sgpr 102
		.amdhsa_accum_offset 256
		.amdhsa_reserve_vcc 1
		.amdhsa_float_round_mode_32 0
		.amdhsa_float_round_mode_16_64 0
		.amdhsa_float_denorm_mode_32 3
		.amdhsa_float_denorm_mode_16_64 3
		.amdhsa_dx10_clamp 1
		.amdhsa_ieee_mode 1
		.amdhsa_fp16_overflow 0
		.amdhsa_tg_split 0
		.amdhsa_exception_fp_ieee_invalid_op 0
		.amdhsa_exception_fp_denorm_src 0
		.amdhsa_exception_fp_ieee_div_zero 0
		.amdhsa_exception_fp_ieee_overflow 0
		.amdhsa_exception_fp_ieee_underflow 0
		.amdhsa_exception_fp_ieee_inexact 0
		.amdhsa_exception_int_div_zero 0
	.end_amdhsa_kernel

amdhsa.kernels:
  - .agpr_count:     0
    .args:
      - .offset:         0
        .size:           192
        .value_kind:     by_value
      - .offset:         192
        .size:           4
        .value_kind:     hidden_block_count_x
      - .offset:         196
        .size:           4
        .value_kind:     hidden_block_count_y
      - .offset:         200
        .size:           4
        .value_kind:     hidden_block_count_z
      - .offset:         204
        .size:           2
        .value_kind:     hidden_group_size_x
      - .offset:         206
        .size:           2
        .value_kind:     hidden_group_size_y
      - .offset:         208
        .size:           2
        .value_kind:     hidden_group_size_z
      - .offset:         210
        .size:           2
        .value_kind:     hidden_remainder_x
      - .offset:         212
        .size:           2
        .value_kind:     hidden_remainder_y
      - .offset:         214
        .size:           2
        .value_kind:     hidden_remainder_z
      - .offset:         232
        .size:           8
        .value_kind:     hidden_global_offset_x
      - .offset:         240
        .size:           8
        .value_kind:     hidden_global_offset_y
      - .offset:         248
        .size:           8
        .value_kind:     hidden_global_offset_z
      - .offset:         256
        .size:           2
        .value_kind:     hidden_grid_dims
      - .offset:         280
        .size:           8
        .value_kind:     hidden_multigrid_sync_arg
      - .offset:         312
        .size:           4
        .value_kind:     hidden_dynamic_lds_size
    .group_segment_fixed_size: 0
    .kernarg_segment_align: 8
    .kernarg_segment_size: 448
    .language:       OpenCL C
    .language_version:
      - 2
      - 0
    .max_flat_workgroup_size: 512
    .name:           _Z6mk_fwd4Args
    .private_segment_fixed_size: 0
    .sgpr_count:     108
    .sgpr_spill_count: 100
    .symbol:         _Z6mk_fwd4Args.kd
    .uniform_work_group_size: 1
    .uses_dynamic_stack: false
    .vgpr_count:     256
    .vgpr_spill_count: 0
    .wavefront_size: 64
